# FFN-in phase start: each wave touches its share of the layer's weight lines so the K loops find them in L2/MALL
# speedup vs baseline: 1.0114x; 1.0022x over previous
; #define BID opqs((int)blockIdx.x)
; template <int E1, int E2>
; DI void gemm_phase2(const GemmP& g1, const GemmP& g2, char* smem) {
;   const int n1 = g1.Mt * g1.Nt, n2 = g2.Mt * g2.Nt;
;   for (int L = BID; L < n1 + n2; L += gridDim.x) {
;     int pm, pn;
;     if (L < n1) { unit_of(L, g1.Mt, g1.Nt, pm, pn); gemm_unit<E1>(g1, pm, pn); }
;     else { unit_of(L - n1, g2.Mt, g2.Nt, pm, pn); gemm_unit<E2>(g2, pm, pn); }
;   }
; DI void run_phase(const Params& p, int ph, char* smem) {
;     ...
;     case 11: {
;       GemmP g1 = mk_gemm(XB, DM, (const u16*)(ws + O_FFIN + L * SZ_FFIN), DM, DM, 64, 44);
;       g1.Cb = (u16*)(ws + O_HID); g1.ldc = FFH;
;       gemm_phase2<EPI_SWIGLU, EPI_SWIGLU>(g1, gz, smem);
;     } break;
.LBB0_147:
	s_andn2_b64 vcc, exec, s[6:7]
	s_cbranch_vccnz .LBB0_157
	v_readlane_b32 s13, v254, 0
	s_cmpk_gt_i32 s13, 0xaff
	s_cbranch_scc1 .LBB0_157
	s_mul_i32 s19, s12, 0x2c00000
	s_mul_hi_i32 s18, s12, 0x2c00000
	s_add_u32 s6, s90, s19
	s_addc_u32 s7, s91, s18
	s_add_u32 s20, s6, 0x9d00000
	s_addc_u32 s21, s7, 0
	s_add_u32 s6, s90, 0x44480000
	s_addc_u32 s7, s91, 0
	v_lshrrev_b32_e32 v2, 6, v201
	v_and_b32_e32 v3, 63, v201
	s_mul_i32 s8, s13, 0x580
	v_mul_u32_u24_e32 v2, 0xb0, v2
	v_add3_u32 v2, v2, v3, s8
	v_lshlrev_b32_e32 v2, 7, v2
	v_add_u32_e32 v7, 0x2000, v2
	v_add_u32_e32 v8, 0x4000, v2
	global_load_dword v4, v2, s[20:21]
	global_load_dword v5, v7, s[20:21]
	v_cmp_gt_u32_e32 vcc, 48, v3
	s_and_saveexec_b64 s[8:9], vcc
	global_load_dword v6, v8, s[20:21]
	s_or_b64 exec, exec, s[8:9]
	s_branch .LBB0_151
